# up main loop: LDS-DMA pieces issued between the MFMAs of the following compute phase, counted waits vmcnt(4)
# speedup vs baseline: 1.0025x; 1.0013x over previous
.LBB0_104:
	s_add_u32 s2, s34, 0xfffc2080
	s_addc_u32 s3, s35, -1
	s_add_i32 s12, 0, 0x10000
	v_add_u32_e32 v110, s12, v179
	ds_read_b128 v[98:101], v110
	ds_read_b128 v[102:105], v110 offset:1024
	ds_read_b128 v[106:109], v110 offset:2048
	ds_read_b128 v[110:113], v110 offset:3072
	s_cmp_eq_u32 s53, 12
	s_cselect_b32 s49, s97, s3
	s_cselect_b32 s48, s96, s2
	s_cselect_b32 s3, s1, s52
	s_cselect_b32 s2, s23, s51
	ds_read_b128 v[114:117], v184
	ds_read_b128 v[118:121], v184 offset:1024
	ds_read_b128 v[122:125], v184 offset:2048
	ds_read_b128 v[126:129], v184 offset:3072
	ds_read_b128 v[186:189], v184 offset:4096
	ds_read_b128 v[190:193], v184 offset:5120
	ds_read_b128 v[194:197], v184 offset:6144
	ds_read_b128 v[198:201], v184 offset:7168
	s_waitcnt lgkmcnt(8)
	s_barrier
	s_waitcnt lgkmcnt(0)
	s_waitcnt lgkmcnt(0)
	v_mfma_f32_16x16x32_bf16 v[158:161], v[98:101], v[114:117], v[158:161]
	v_mfma_f32_16x16x32_bf16 v[154:157], v[106:109], v[114:117], v[154:157]
	v_mfma_f32_16x16x32_bf16 v[150:153], v[98:101], v[122:125], v[150:153]
	v_lshl_add_u64 v[174:175], s[34:35], 0, v[170:171]
	s_add_i32 m0, s85, 0xc000
	v_mfma_f32_16x16x32_bf16 v[146:149], v[106:109], v[122:125], v[146:149]
	global_load_lds_dwordx4 v[174:175], off
	v_mfma_f32_16x16x32_bf16 v[142:145], v[98:101], v[186:189], v[142:145]
	v_mfma_f32_16x16x32_bf16 v[138:141], v[106:109], v[186:189], v[138:141]
	v_mfma_f32_16x16x32_bf16 v[134:137], v[98:101], v[194:197], v[134:137]
	v_mfma_f32_16x16x32_bf16 v[130:133], v[106:109], v[194:197], v[130:133]
	v_mfma_f32_16x16x32_bf16 v[158:161], v[102:105], v[118:121], v[158:161]
	v_lshl_add_u64 v[174:175], s[34:35], 0, v[172:173]
	s_add_i32 m0, s85, 0xe000
	v_mfma_f32_16x16x32_bf16 v[154:157], v[110:113], v[118:121], v[154:157]
	global_load_lds_dwordx4 v[174:175], off
	v_mfma_f32_16x16x32_bf16 v[150:153], v[102:105], v[126:129], v[150:153]
	v_mfma_f32_16x16x32_bf16 v[146:149], v[110:113], v[126:129], v[146:149]
	v_mfma_f32_16x16x32_bf16 v[142:145], v[102:105], v[190:193], v[142:145]
	v_mfma_f32_16x16x32_bf16 v[138:141], v[110:113], v[190:193], v[138:141]
	v_mfma_f32_16x16x32_bf16 v[134:137], v[102:105], v[198:201], v[134:137]
	v_mfma_f32_16x16x32_bf16 v[130:133], v[110:113], v[198:201], v[130:133]
	s_barrier
	s_add_i32 s54, 0, 0x14000
	v_add_u32_e32 v174, s54, v179
	s_add_i32 s12, s12, s78
	ds_read_b128 v[226:229], v174
	ds_read_b128 v[230:233], v174 offset:1024
	ds_read_b128 v[234:237], v174 offset:2048
	ds_read_b128 v[242:245], v174 offset:3072
	s_barrier
	s_waitcnt lgkmcnt(0)
	s_waitcnt lgkmcnt(0)
	v_mfma_f32_16x16x32_bf16 v[62:65], v[226:229], v[114:117], v[62:65]
	v_mfma_f32_16x16x32_bf16 v[58:61], v[234:237], v[114:117], v[58:61]
	v_mfma_f32_16x16x32_bf16 v[54:57], v[226:229], v[122:125], v[54:57]
	v_lshl_add_u64 v[174:175], s[2:3], 0, v[0:1]
	s_mov_b32 m0, s12
	v_lshl_add_u64 v[246:247], s[2:3], 0, v[166:167]
	v_mfma_f32_16x16x32_bf16 v[50:53], v[234:237], v[122:125], v[50:53]
	global_load_lds_dwordx4 v[174:175], off
	v_mfma_f32_16x16x32_bf16 v[46:49], v[226:229], v[186:189], v[46:49]
	v_mfma_f32_16x16x32_bf16 v[42:45], v[234:237], v[186:189], v[42:45]
	v_mfma_f32_16x16x32_bf16 v[38:41], v[226:229], v[194:197], v[38:41]
	v_mfma_f32_16x16x32_bf16 v[34:37], v[234:237], v[194:197], v[34:37]
	v_mfma_f32_16x16x32_bf16 v[62:65], v[230:233], v[118:121], v[62:65]
	s_add_i32 m0, s12, 0x2000
	v_mfma_f32_16x16x32_bf16 v[58:61], v[242:245], v[118:121], v[58:61]
	global_load_lds_dwordx4 v[246:247], off
	v_mfma_f32_16x16x32_bf16 v[54:57], v[230:233], v[126:129], v[54:57]
	v_mfma_f32_16x16x32_bf16 v[50:53], v[242:245], v[126:129], v[50:53]
	v_mfma_f32_16x16x32_bf16 v[46:49], v[230:233], v[190:193], v[46:49]
	v_mfma_f32_16x16x32_bf16 v[42:45], v[242:245], v[190:193], v[42:45]
	v_mfma_f32_16x16x32_bf16 v[38:41], v[230:233], v[198:201], v[38:41]
	v_mfma_f32_16x16x32_bf16 v[34:37], v[242:245], v[198:201], v[34:37]
	s_mov_b32 m0, s85
	v_lshl_add_u64 v[248:249], s[48:49], 0, v[162:163]
	s_barrier
	ds_read_b128 v[114:117], v184 offset:16384
	ds_read_b128 v[118:121], v184 offset:17408
	ds_read_b128 v[122:125], v184 offset:18432
	ds_read_b128 v[126:129], v184 offset:19456
	ds_read_b128 v[186:189], v184 offset:20480
	ds_read_b128 v[190:193], v184 offset:21504
	ds_read_b128 v[194:197], v184 offset:22528
	ds_read_b128 v[198:201], v184 offset:23552
	s_barrier
	s_waitcnt lgkmcnt(0)
	s_waitcnt lgkmcnt(0)
	v_mfma_f32_16x16x32_bf16 v[94:97], v[98:101], v[114:117], v[94:97]
	v_mfma_f32_16x16x32_bf16 v[90:93], v[106:109], v[114:117], v[90:93]
	v_mfma_f32_16x16x32_bf16 v[86:89], v[98:101], v[122:125], v[86:89]
	v_mfma_f32_16x16x32_bf16 v[82:85], v[106:109], v[122:125], v[82:85]
	global_load_lds_dwordx4 v[248:249], off
	v_mfma_f32_16x16x32_bf16 v[78:81], v[98:101], v[186:189], v[78:81]
	v_mfma_f32_16x16x32_bf16 v[74:77], v[106:109], v[186:189], v[74:77]
	v_mfma_f32_16x16x32_bf16 v[70:73], v[98:101], v[194:197], v[70:73]
	v_mfma_f32_16x16x32_bf16 v[66:69], v[106:109], v[194:197], v[66:69]
	v_mfma_f32_16x16x32_bf16 v[94:97], v[102:105], v[118:121], v[94:97]
	v_lshl_add_u64 v[250:251], s[48:49], 0, v[164:165]
	s_mov_b32 m0, s82
	v_mfma_f32_16x16x32_bf16 v[90:93], v[110:113], v[118:121], v[90:93]
	global_load_lds_dwordx4 v[250:251], off
	v_mfma_f32_16x16x32_bf16 v[86:89], v[102:105], v[126:129], v[86:89]
	v_mfma_f32_16x16x32_bf16 v[82:85], v[110:113], v[126:129], v[82:85]
	v_mfma_f32_16x16x32_bf16 v[78:81], v[102:105], v[190:193], v[78:81]
	v_mfma_f32_16x16x32_bf16 v[74:77], v[110:113], v[190:193], v[74:77]
	v_mfma_f32_16x16x32_bf16 v[70:73], v[102:105], v[198:201], v[70:73]
	v_mfma_f32_16x16x32_bf16 v[66:69], v[110:113], v[198:201], v[66:69]
	s_barrier
	s_add_u32 s12, s2, 0x40000
	s_addc_u32 s13, s3, 0
	s_add_i32 s54, s54, s78
	s_waitcnt vmcnt(4)
	s_barrier
	v_mfma_f32_16x16x32_bf16 v[30:33], v[226:229], v[114:117], v[30:33]
	v_mfma_f32_16x16x32_bf16 v[26:29], v[234:237], v[114:117], v[26:29]
	v_mfma_f32_16x16x32_bf16 v[22:25], v[226:229], v[122:125], v[22:25]
	v_lshl_add_u64 v[98:99], s[12:13], 0, v[0:1]
	s_mov_b32 m0, s54
	v_mfma_f32_16x16x32_bf16 v[18:21], v[234:237], v[122:125], v[18:21]
	global_load_lds_dwordx4 v[98:99], off
	v_mfma_f32_16x16x32_bf16 v[14:17], v[226:229], v[186:189], v[14:17]
	v_mfma_f32_16x16x32_bf16 v[10:13], v[234:237], v[186:189], v[10:13]
	v_mfma_f32_16x16x32_bf16 v[6:9], v[226:229], v[194:197], v[6:9]
	v_mfma_f32_16x16x32_bf16 v[2:5], v[234:237], v[194:197], v[2:5]
	v_mfma_f32_16x16x32_bf16 v[30:33], v[230:233], v[118:121], v[30:33]
	v_lshl_add_u64 v[98:99], s[12:13], 0, v[166:167]
	s_add_i32 m0, s54, 0x2000
	v_mfma_f32_16x16x32_bf16 v[26:29], v[242:245], v[118:121], v[26:29]
	global_load_lds_dwordx4 v[98:99], off
	v_mfma_f32_16x16x32_bf16 v[22:25], v[230:233], v[126:129], v[22:25]
	v_mfma_f32_16x16x32_bf16 v[18:21], v[242:245], v[126:129], v[18:21]
	v_mfma_f32_16x16x32_bf16 v[14:17], v[230:233], v[190:193], v[14:17]
	v_mfma_f32_16x16x32_bf16 v[10:13], v[242:245], v[190:193], v[10:13]
	v_mfma_f32_16x16x32_bf16 v[6:9], v[230:233], v[198:201], v[6:9]
	v_mfma_f32_16x16x32_bf16 v[2:5], v[242:245], v[198:201], v[2:5]
	s_add_i32 s54, 0, 0x18000
	v_add_u32_e32 v110, s54, v179
	s_barrier
	ds_read_b128 v[98:101], v110
	ds_read_b128 v[102:105], v110 offset:1024
	ds_read_b128 v[106:109], v110 offset:2048
	ds_read_b128 v[110:113], v110 offset:3072
	s_add_u32 s12, s48, 0x3e000
	s_addc_u32 s13, s49, 0
	ds_read_b128 v[114:117], v184 offset:32768
	ds_read_b128 v[118:121], v184 offset:33792
	ds_read_b128 v[122:125], v184 offset:34816
	ds_read_b128 v[126:129], v184 offset:35840
	ds_read_b128 v[186:189], v184 offset:36864
	ds_read_b128 v[190:193], v184 offset:37888
	ds_read_b128 v[194:197], v184 offset:38912
	ds_read_b128 v[198:201], v184 offset:39936
	s_waitcnt lgkmcnt(8)
	s_barrier
	s_waitcnt lgkmcnt(0)
	s_waitcnt lgkmcnt(0)
	v_mfma_f32_16x16x32_bf16 v[158:161], v[98:101], v[114:117], v[158:161]
	v_mfma_f32_16x16x32_bf16 v[154:157], v[106:109], v[114:117], v[154:157]
	v_mfma_f32_16x16x32_bf16 v[150:153], v[98:101], v[122:125], v[150:153]
	s_mov_b32 m0, s89
	v_lshl_add_u64 v[226:227], s[12:13], 0, v[162:163]
	v_mfma_f32_16x16x32_bf16 v[146:149], v[106:109], v[122:125], v[146:149]
	global_load_lds_dwordx4 v[226:227], off
	v_mfma_f32_16x16x32_bf16 v[142:145], v[98:101], v[186:189], v[142:145]
	v_mfma_f32_16x16x32_bf16 v[138:141], v[106:109], v[186:189], v[138:141]
	v_mfma_f32_16x16x32_bf16 v[134:137], v[98:101], v[194:197], v[134:137]
	v_mfma_f32_16x16x32_bf16 v[130:133], v[106:109], v[194:197], v[130:133]
	v_mfma_f32_16x16x32_bf16 v[158:161], v[102:105], v[118:121], v[158:161]
	v_lshl_add_u64 v[226:227], s[12:13], 0, v[164:165]
	s_mov_b32 m0, s91
	v_mfma_f32_16x16x32_bf16 v[154:157], v[110:113], v[118:121], v[154:157]
	global_load_lds_dwordx4 v[226:227], off
	v_mfma_f32_16x16x32_bf16 v[150:153], v[102:105], v[126:129], v[150:153]
	v_mfma_f32_16x16x32_bf16 v[146:149], v[110:113], v[126:129], v[146:149]
	v_mfma_f32_16x16x32_bf16 v[142:145], v[102:105], v[190:193], v[142:145]
	v_mfma_f32_16x16x32_bf16 v[138:141], v[110:113], v[190:193], v[138:141]
	v_mfma_f32_16x16x32_bf16 v[134:137], v[102:105], v[198:201], v[134:137]
	v_mfma_f32_16x16x32_bf16 v[130:133], v[110:113], v[198:201], v[130:133]
	s_barrier
	s_add_i32 s12, 0, 0x1c000
	s_add_i32 s13, s54, s78
	v_add_u32_e32 v242, s12, v179
	ds_read_b128 v[226:229], v242
	ds_read_b128 v[230:233], v242 offset:1024
	ds_read_b128 v[234:237], v242 offset:2048
	ds_read_b128 v[242:245], v242 offset:3072
	s_barrier
	s_waitcnt lgkmcnt(0)
	s_waitcnt lgkmcnt(0)
	v_mfma_f32_16x16x32_bf16 v[62:65], v[226:229], v[114:117], v[62:65]
	v_mfma_f32_16x16x32_bf16 v[58:61], v[234:237], v[114:117], v[58:61]
	v_mfma_f32_16x16x32_bf16 v[54:57], v[226:229], v[122:125], v[54:57]
	v_lshl_add_u64 v[174:175], v[174:175], 0, s[20:21]
	s_mov_b32 m0, s13
	v_mfma_f32_16x16x32_bf16 v[50:53], v[234:237], v[122:125], v[50:53]
	global_load_lds_dwordx4 v[174:175], off
	v_mfma_f32_16x16x32_bf16 v[46:49], v[226:229], v[186:189], v[46:49]
	v_mfma_f32_16x16x32_bf16 v[42:45], v[234:237], v[186:189], v[42:45]
	v_mfma_f32_16x16x32_bf16 v[38:41], v[226:229], v[194:197], v[38:41]
	v_mfma_f32_16x16x32_bf16 v[34:37], v[234:237], v[194:197], v[34:37]
	v_mfma_f32_16x16x32_bf16 v[62:65], v[230:233], v[118:121], v[62:65]
	v_lshl_add_u64 v[174:175], v[246:247], 0, s[20:21]
	s_add_i32 m0, s13, 0x2000
	v_mfma_f32_16x16x32_bf16 v[58:61], v[242:245], v[118:121], v[58:61]
	global_load_lds_dwordx4 v[174:175], off
	v_mfma_f32_16x16x32_bf16 v[54:57], v[230:233], v[126:129], v[54:57]
	v_mfma_f32_16x16x32_bf16 v[50:53], v[242:245], v[126:129], v[50:53]
	v_mfma_f32_16x16x32_bf16 v[46:49], v[230:233], v[190:193], v[46:49]
	v_mfma_f32_16x16x32_bf16 v[42:45], v[242:245], v[190:193], v[42:45]
	v_mfma_f32_16x16x32_bf16 v[38:41], v[230:233], v[198:201], v[38:41]
	v_mfma_f32_16x16x32_bf16 v[34:37], v[242:245], v[198:201], v[34:37]
	s_mov_b32 m0, s79
	v_lshl_add_u64 v[174:175], v[248:249], 0, s[20:21]
	s_barrier
	ds_read_b128 v[114:117], v184 offset:49152
	ds_read_b128 v[118:121], v184 offset:50176
	ds_read_b128 v[122:125], v184 offset:51200
	ds_read_b128 v[126:129], v184 offset:52224
	ds_read_b128 v[186:189], v184 offset:53248
	ds_read_b128 v[190:193], v184 offset:54272
	ds_read_b128 v[194:197], v184 offset:55296
	ds_read_b128 v[198:201], v184 offset:56320
	s_barrier
	s_waitcnt lgkmcnt(0)
	s_waitcnt lgkmcnt(0)
	v_mfma_f32_16x16x32_bf16 v[94:97], v[98:101], v[114:117], v[94:97]
	v_mfma_f32_16x16x32_bf16 v[90:93], v[106:109], v[114:117], v[90:93]
	v_mfma_f32_16x16x32_bf16 v[86:89], v[98:101], v[122:125], v[86:89]
	v_mfma_f32_16x16x32_bf16 v[82:85], v[106:109], v[122:125], v[82:85]
	global_load_lds_dwordx4 v[174:175], off
	v_mfma_f32_16x16x32_bf16 v[78:81], v[98:101], v[186:189], v[78:81]
	v_mfma_f32_16x16x32_bf16 v[74:77], v[106:109], v[186:189], v[74:77]
	v_mfma_f32_16x16x32_bf16 v[70:73], v[98:101], v[194:197], v[70:73]
	v_mfma_f32_16x16x32_bf16 v[66:69], v[106:109], v[194:197], v[66:69]
	v_mfma_f32_16x16x32_bf16 v[94:97], v[102:105], v[118:121], v[94:97]
	v_lshl_add_u64 v[174:175], v[250:251], 0, s[20:21]
	s_mov_b32 m0, s87
	v_mfma_f32_16x16x32_bf16 v[90:93], v[110:113], v[118:121], v[90:93]
	global_load_lds_dwordx4 v[174:175], off
	v_mfma_f32_16x16x32_bf16 v[86:89], v[102:105], v[126:129], v[86:89]
	v_mfma_f32_16x16x32_bf16 v[82:85], v[110:113], v[126:129], v[82:85]
	v_mfma_f32_16x16x32_bf16 v[78:81], v[102:105], v[190:193], v[78:81]
	v_mfma_f32_16x16x32_bf16 v[74:77], v[110:113], v[190:193], v[74:77]
	v_mfma_f32_16x16x32_bf16 v[70:73], v[102:105], v[198:201], v[70:73]
	v_mfma_f32_16x16x32_bf16 v[66:69], v[110:113], v[198:201], v[66:69]
	s_barrier
	s_add_u32 s2, s2, 0x40080
	s_addc_u32 s3, s3, 0
	s_add_i32 s12, s12, s78
	s_waitcnt vmcnt(4)
	s_barrier
	v_mfma_f32_16x16x32_bf16 v[30:33], v[226:229], v[114:117], v[30:33]
	v_mfma_f32_16x16x32_bf16 v[26:29], v[234:237], v[114:117], v[26:29]
	v_mfma_f32_16x16x32_bf16 v[22:25], v[226:229], v[122:125], v[22:25]
	v_lshl_add_u64 v[98:99], s[2:3], 0, v[0:1]
	s_mov_b32 m0, s12
	v_mfma_f32_16x16x32_bf16 v[18:21], v[234:237], v[122:125], v[18:21]
	global_load_lds_dwordx4 v[98:99], off
	v_mfma_f32_16x16x32_bf16 v[14:17], v[226:229], v[186:189], v[14:17]
	v_mfma_f32_16x16x32_bf16 v[10:13], v[234:237], v[186:189], v[10:13]
	v_mfma_f32_16x16x32_bf16 v[6:9], v[226:229], v[194:197], v[6:9]
	v_mfma_f32_16x16x32_bf16 v[2:5], v[234:237], v[194:197], v[2:5]
	v_mfma_f32_16x16x32_bf16 v[30:33], v[230:233], v[118:121], v[30:33]
	v_lshl_add_u64 v[98:99], s[2:3], 0, v[166:167]
	s_add_i32 m0, s12, 0x2000
	v_mfma_f32_16x16x32_bf16 v[26:29], v[242:245], v[118:121], v[26:29]
	global_load_lds_dwordx4 v[98:99], off
	v_mfma_f32_16x16x32_bf16 v[22:25], v[230:233], v[126:129], v[22:25]
	v_mfma_f32_16x16x32_bf16 v[18:21], v[242:245], v[126:129], v[18:21]
	v_mfma_f32_16x16x32_bf16 v[14:17], v[230:233], v[190:193], v[14:17]
	v_mfma_f32_16x16x32_bf16 v[10:13], v[242:245], v[190:193], v[10:13]
	v_mfma_f32_16x16x32_bf16 v[6:9], v[230:233], v[198:201], v[6:9]
	v_mfma_f32_16x16x32_bf16 v[2:5], v[242:245], v[198:201], v[2:5]
	s_add_i32 s53, s53, 2
	s_add_u32 s34, s34, 0x100
	s_addc_u32 s35, s35, 0
	s_add_u32 s51, s51, 0x100
	s_addc_u32 s52, s52, 0
	s_cmp_gt_u32 s53, 13
	s_barrier
	s_cbranch_scc0 .LBB0_104
	s_add_i32 s1, s50, 0xffffffbd
	s_cmpk_gt_i32 s50, 0x42
	s_cselect_b32 s1, s1, s50
	s_mul_i32 s23, s1, 0xf8
	s_cselect_b32 s2, 0x4000, 0
	s_cselect_b32 s3, 0x100, s37
	s_add_i32 s23, s23, s84
	v_add_u32_e32 v188, s88, v178
	ds_read_b128 v[126:129], v188
	ds_read_b128 v[122:125], v188 offset:128
	ds_read_b128 v[114:117], v188 offset:256
	ds_read_b128 v[118:121], v188 offset:384
	ds_read_b128 v[110:113], v188 offset:512
	ds_read_b128 v[106:109], v188 offset:640
	ds_read_b128 v[98:101], v188 offset:768
	ds_read_b128 v[102:105], v188 offset:896
	v_readlane_b32 s12, v252, 28
	v_readlane_b32 s13, v252, 29
	v_bfe_u32 v231, v202, 5, 1
	v_and_b32_e32 v174, 48, v180
	v_lshl_or_b32 v174, v231, 3, v174
	v_lshl_or_b32 v174, s0, 7, v174
	v_bfe_u32 v230, v202, 4, 1
	v_lshl_add_u32 v186, v177, 2, s23
	v_cmp_eq_u32_e32 vcc, 1, v230
	s_or_b64 s[52:53], s[42:43], vcc
	v_cmp_eq_u32_e32 vcc, 0, v230
	s_or_b64 s[54:55], s[44:45], vcc
	v_add_u32_e32 v186, v186, v230
	v_add_u32_e32 v187, s2, v186
	v_mul_u32_u24_e32 v187, 0x1600, v187
	v_lshl_add_u32 v187, v174, 1, v187
	s_waitcnt lgkmcnt(0)
	v_fma_f32 v190, v158, v122, v118
	v_fma_f32 v191, v159, v123, v119
	v_fma_f32 v192, v160, v124, v120
	v_fma_f32 v193, v161, v125, v121
	v_fma_f32 v194, v154, v106, v102
	v_fma_f32 v195, v155, v107, v103
	v_fma_f32 v196, v156, v108, v104
	v_fma_f32 v197, v157, v109, v105
	v_add_u32_e32 v230, 0, v186
	v_fmac_f32_dpp v190, v134, v126 row_ror:1 row_mask:0xf bank_mask:0xf
	v_fmac_f32_dpp v191, v135, v127 row_ror:1 row_mask:0xf bank_mask:0xf
	v_fmac_f32_dpp v192, v136, v128 row_ror:1 row_mask:0xf bank_mask:0xf
	v_fmac_f32_dpp v193, v137, v129 row_ror:1 row_mask:0xf bank_mask:0xf
	v_fmac_f32_dpp v194, v130, v110 row_ror:1 row_mask:0xf bank_mask:0xf
	v_fmac_f32_dpp v195, v131, v111 row_ror:1 row_mask:0xf bank_mask:0xf
	v_fmac_f32_dpp v196, v132, v112 row_ror:1 row_mask:0xf bank_mask:0xf
	v_fmac_f32_dpp v197, v133, v113 row_ror:1 row_mask:0xf bank_mask:0xf
	v_fmac_f32_e32 v190, v150, v114
	v_fmac_f32_e32 v191, v151, v115
	v_fmac_f32_e32 v192, v152, v116
	v_fmac_f32_e32 v193, v153, v117
	v_fmac_f32_e32 v194, v146, v98
	v_fmac_f32_e32 v195, v147, v99
	v_fmac_f32_e32 v196, v148, v100
	v_fmac_f32_e32 v197, v149, v101
	v_mul_f32_e32 v198, 0xbfb8aa3b, v190
	v_mul_f32_e32 v199, 0xbfb8aa3b, v191
	v_mul_f32_e32 v200, 0xbfb8aa3b, v192
	v_mul_f32_e32 v201, 0xbfb8aa3b, v193
	v_exp_f32_e32 v198, v198
	v_exp_f32_e32 v199, v199
	v_exp_f32_e32 v200, v200
	v_exp_f32_e32 v201, v201
	v_add_f32_e32 v198, 1.0, v198
	v_add_f32_e32 v199, 1.0, v199
	v_add_f32_e32 v200, 1.0, v200
	v_add_f32_e32 v201, 1.0, v201
	v_rcp_f32_e32 v198, v198
	v_rcp_f32_e32 v199, v199
	v_rcp_f32_e32 v200, v200
	v_rcp_f32_e32 v201, v201
	v_mul_f32_e32 v190, v190, v198
	v_mul_f32_e32 v191, v191, v199
	v_mul_f32_e32 v192, v192, v200
	v_mul_f32_e32 v193, v193, v201
	v_mul_f32_e32 v190, v190, v194
	v_mul_f32_e32 v191, v191, v195
	v_mul_f32_e32 v192, v192, v196
	v_mul_f32_e32 v193, v193, v197
	v_cvt_pk_bf16_f32 v232, v190, v191
	v_cvt_pk_bf16_f32 v233, v192, v193
	v_fma_f32 v190, v150, v122, v118
	v_fma_f32 v191, v151, v123, v119
	v_fma_f32 v192, v152, v124, v120
	v_fma_f32 v193, v153, v125, v121
	v_fma_f32 v194, v146, v106, v102
	v_fma_f32 v195, v147, v107, v103
	v_fma_f32 v196, v148, v108, v104
	v_fma_f32 v197, v149, v109, v105
	v_fmac_f32_e32 v190, v158, v126
	v_fmac_f32_e32 v191, v159, v127
	v_fmac_f32_e32 v192, v160, v128
	v_fmac_f32_e32 v193, v161, v129
	v_fmac_f32_e32 v194, v154, v110
	v_fmac_f32_e32 v195, v155, v111
	v_fmac_f32_e32 v196, v156, v112
	v_fmac_f32_e32 v197, v157, v113
	v_fmac_f32_e32 v190, v142, v114
	v_fmac_f32_e32 v191, v143, v115
	v_fmac_f32_e32 v192, v144, v116
	v_fmac_f32_e32 v193, v145, v117
	v_fmac_f32_e32 v194, v138, v98
	v_fmac_f32_e32 v195, v139, v99
	v_fmac_f32_e32 v196, v140, v100
	v_fmac_f32_e32 v197, v141, v101
	v_mul_f32_e32 v198, 0xbfb8aa3b, v190
	v_mul_f32_e32 v199, 0xbfb8aa3b, v191
	v_mul_f32_e32 v200, 0xbfb8aa3b, v192
	v_mul_f32_e32 v201, 0xbfb8aa3b, v193
	v_exp_f32_e32 v198, v198
	v_exp_f32_e32 v199, v199
	v_exp_f32_e32 v200, v200
	v_exp_f32_e32 v201, v201
	v_add_f32_e32 v198, 1.0, v198
	v_add_f32_e32 v199, 1.0, v199
	v_add_f32_e32 v200, 1.0, v200
	v_add_f32_e32 v201, 1.0, v201
	v_rcp_f32_e32 v198, v198
	v_rcp_f32_e32 v199, v199
	v_rcp_f32_e32 v200, v200
	v_rcp_f32_e32 v201, v201
	v_mul_f32_e32 v190, v190, v198
	v_mul_f32_e32 v191, v191, v199
	v_mul_f32_e32 v192, v192, v200
	v_mul_f32_e32 v193, v193, v201
	v_mul_f32_e32 v190, v190, v194
	v_mul_f32_e32 v191, v191, v195
	v_mul_f32_e32 v192, v192, v196
	v_mul_f32_e32 v193, v193, v197
	v_cvt_pk_bf16_f32 v234, v190, v191
	v_cvt_pk_bf16_f32 v235, v192, v193
	v_cmp_gt_i32_e32 vcc, s3, v230
	s_and_b64 vcc, vcc, s[52:53]
	s_nop 0
	v_permlane16_swap_b32_e32 v232, v234
	v_permlane16_swap_b32_e32 v233, v235
	s_and_saveexec_b64 s[0:1], vcc
	global_store_dwordx4 v187, v[232:235], s[12:13]
	s_mov_b64 exec, s[0:1]
	v_fma_f32 v190, v142, v122, v118
	v_fma_f32 v191, v143, v123, v119
	v_fma_f32 v192, v144, v124, v120
	v_fma_f32 v193, v145, v125, v121
	v_fma_f32 v194, v138, v106, v102
	v_fma_f32 v195, v139, v107, v103
	v_fma_f32 v196, v140, v108, v104
	v_fma_f32 v197, v141, v109, v105
	v_add_u32_e32 v230, 2, v186
	v_add_u32_e32 v231, 0x2c00, v187
	v_fmac_f32_e32 v190, v150, v126
	v_fmac_f32_e32 v191, v151, v127
	v_fmac_f32_e32 v192, v152, v128
	v_fmac_f32_e32 v193, v153, v129
	v_fmac_f32_e32 v194, v146, v110
	v_fmac_f32_e32 v195, v147, v111
	v_fmac_f32_e32 v196, v148, v112
	v_fmac_f32_e32 v197, v149, v113
	v_fmac_f32_e32 v190, v134, v114
	v_fmac_f32_e32 v191, v135, v115
	v_fmac_f32_e32 v192, v136, v116
	v_fmac_f32_e32 v193, v137, v117
	v_fmac_f32_e32 v194, v130, v98
	v_fmac_f32_e32 v195, v131, v99
	v_fmac_f32_e32 v196, v132, v100
	v_fmac_f32_e32 v197, v133, v101
	v_mul_f32_e32 v198, 0xbfb8aa3b, v190
	v_mul_f32_e32 v199, 0xbfb8aa3b, v191
	v_mul_f32_e32 v200, 0xbfb8aa3b, v192
	v_mul_f32_e32 v201, 0xbfb8aa3b, v193
	v_exp_f32_e32 v198, v198
	v_exp_f32_e32 v199, v199
	v_exp_f32_e32 v200, v200
	v_exp_f32_e32 v201, v201
	v_add_f32_e32 v198, 1.0, v198
	v_add_f32_e32 v199, 1.0, v199
	v_add_f32_e32 v200, 1.0, v200
	v_add_f32_e32 v201, 1.0, v201
	v_rcp_f32_e32 v198, v198
	v_rcp_f32_e32 v199, v199
	v_rcp_f32_e32 v200, v200
	v_rcp_f32_e32 v201, v201
	v_mul_f32_e32 v190, v190, v198
	v_mul_f32_e32 v191, v191, v199
	v_mul_f32_e32 v192, v192, v200
	v_mul_f32_e32 v193, v193, v201
	v_mul_f32_e32 v190, v190, v194
	v_mul_f32_e32 v191, v191, v195
	v_mul_f32_e32 v192, v192, v196
	v_mul_f32_e32 v193, v193, v197
	v_cvt_pk_bf16_f32 v232, v190, v191
	v_cvt_pk_bf16_f32 v233, v192, v193
	v_fma_f32 v190, v134, v122, v118
	v_fma_f32 v191, v135, v123, v119
	v_fma_f32 v192, v136, v124, v120
	v_fma_f32 v193, v137, v125, v121
	v_fma_f32 v194, v130, v106, v102
	v_fma_f32 v195, v131, v107, v103
	v_fma_f32 v196, v132, v108, v104
	v_fma_f32 v197, v133, v109, v105
	v_fmac_f32_e32 v190, v142, v126
	v_fmac_f32_e32 v191, v143, v127
	v_fmac_f32_e32 v192, v144, v128
	v_fmac_f32_e32 v193, v145, v129
	v_fmac_f32_e32 v194, v138, v110
	v_fmac_f32_e32 v195, v139, v111
	v_fmac_f32_e32 v196, v140, v112
	v_fmac_f32_e32 v197, v141, v113
	v_fmac_f32_dpp v190, v158, v114 row_ror:15 row_mask:0xf bank_mask:0xf
	v_fmac_f32_dpp v191, v159, v115 row_ror:15 row_mask:0xf bank_mask:0xf
	v_fmac_f32_dpp v192, v160, v116 row_ror:15 row_mask:0xf bank_mask:0xf
	v_fmac_f32_dpp v193, v161, v117 row_ror:15 row_mask:0xf bank_mask:0xf
	v_fmac_f32_dpp v194, v154, v98 row_ror:15 row_mask:0xf bank_mask:0xf
	v_fmac_f32_dpp v195, v155, v99 row_ror:15 row_mask:0xf bank_mask:0xf
	v_fmac_f32_dpp v196, v156, v100 row_ror:15 row_mask:0xf bank_mask:0xf
	v_fmac_f32_dpp v197, v157, v101 row_ror:15 row_mask:0xf bank_mask:0xf
	v_mul_f32_e32 v198, 0xbfb8aa3b, v190
	v_mul_f32_e32 v199, 0xbfb8aa3b, v191
	v_mul_f32_e32 v200, 0xbfb8aa3b, v192
	v_mul_f32_e32 v201, 0xbfb8aa3b, v193
	v_exp_f32_e32 v198, v198
	v_exp_f32_e32 v199, v199
	v_exp_f32_e32 v200, v200
	v_exp_f32_e32 v201, v201
	v_add_f32_e32 v198, 1.0, v198
	v_add_f32_e32 v199, 1.0, v199
	v_add_f32_e32 v200, 1.0, v200
	v_add_f32_e32 v201, 1.0, v201
	v_rcp_f32_e32 v198, v198
	v_rcp_f32_e32 v199, v199
	v_rcp_f32_e32 v200, v200
	v_rcp_f32_e32 v201, v201
	v_mul_f32_e32 v190, v190, v198
	v_mul_f32_e32 v191, v191, v199
	v_mul_f32_e32 v192, v192, v200
	v_mul_f32_e32 v193, v193, v201
	v_mul_f32_e32 v190, v190, v194
	v_mul_f32_e32 v191, v191, v195
	v_mul_f32_e32 v192, v192, v196
	v_mul_f32_e32 v193, v193, v197
	v_cvt_pk_bf16_f32 v234, v190, v191
	v_cvt_pk_bf16_f32 v235, v192, v193
	v_cmp_gt_i32_e32 vcc, s3, v230
	s_and_b64 vcc, vcc, s[54:55]
	s_nop 0
	v_permlane16_swap_b32_e32 v232, v234
	v_permlane16_swap_b32_e32 v233, v235
	s_and_saveexec_b64 s[0:1], vcc
	global_store_dwordx4 v231, v[232:235], s[12:13]
	s_mov_b64 exec, s[0:1]
	ds_read_b128 v[130:133], v188 offset:64
	ds_read_b128 v[134:137], v188 offset:192
	ds_read_b128 v[138:141], v188 offset:320
	ds_read_b128 v[142:145], v188 offset:448
	ds_read_b128 v[146:149], v188 offset:576
	ds_read_b128 v[150:153], v188 offset:704
	ds_read_b128 v[154:157], v188 offset:832
	ds_read_b128 v[158:161], v188 offset:960
	v_fma_f32 v190, v94, v122, v118
	v_fma_f32 v191, v95, v123, v119
	v_fma_f32 v192, v96, v124, v120
	v_fma_f32 v193, v97, v125, v121
	v_fma_f32 v194, v90, v106, v102
	v_fma_f32 v195, v91, v107, v103
	v_fma_f32 v196, v92, v108, v104
	v_fma_f32 v197, v93, v109, v105
	v_add_u32_e32 v230, 0x7c, v186
	v_add_u32_e32 v231, 0xaa800, v187
	v_fmac_f32_dpp v190, v70, v126 row_ror:1 row_mask:0xf bank_mask:0xf
	v_fmac_f32_dpp v191, v71, v127 row_ror:1 row_mask:0xf bank_mask:0xf
	v_fmac_f32_dpp v192, v72, v128 row_ror:1 row_mask:0xf bank_mask:0xf
	v_fmac_f32_dpp v193, v73, v129 row_ror:1 row_mask:0xf bank_mask:0xf
	v_fmac_f32_dpp v194, v66, v110 row_ror:1 row_mask:0xf bank_mask:0xf
	v_fmac_f32_dpp v195, v67, v111 row_ror:1 row_mask:0xf bank_mask:0xf
	v_fmac_f32_dpp v196, v68, v112 row_ror:1 row_mask:0xf bank_mask:0xf
	v_fmac_f32_dpp v197, v69, v113 row_ror:1 row_mask:0xf bank_mask:0xf
	v_fmac_f32_e32 v190, v86, v114
	v_fmac_f32_e32 v191, v87, v115
	v_fmac_f32_e32 v192, v88, v116
	v_fmac_f32_e32 v193, v89, v117
	v_fmac_f32_e32 v194, v82, v98
	v_fmac_f32_e32 v195, v83, v99
	v_fmac_f32_e32 v196, v84, v100
	v_fmac_f32_e32 v197, v85, v101
	v_mul_f32_e32 v198, 0xbfb8aa3b, v190
	v_mul_f32_e32 v199, 0xbfb8aa3b, v191
	v_mul_f32_e32 v200, 0xbfb8aa3b, v192
	v_mul_f32_e32 v201, 0xbfb8aa3b, v193
	v_exp_f32_e32 v198, v198
	v_exp_f32_e32 v199, v199
	v_exp_f32_e32 v200, v200
	v_exp_f32_e32 v201, v201
	v_add_f32_e32 v198, 1.0, v198
	v_add_f32_e32 v199, 1.0, v199
	v_add_f32_e32 v200, 1.0, v200
	v_add_f32_e32 v201, 1.0, v201
	v_rcp_f32_e32 v198, v198
	v_rcp_f32_e32 v199, v199
	v_rcp_f32_e32 v200, v200
	v_rcp_f32_e32 v201, v201
	v_mul_f32_e32 v190, v190, v198
	v_mul_f32_e32 v191, v191, v199
	v_mul_f32_e32 v192, v192, v200
	v_mul_f32_e32 v193, v193, v201
	v_mul_f32_e32 v190, v190, v194
	v_mul_f32_e32 v191, v191, v195
	v_mul_f32_e32 v192, v192, v196
	v_mul_f32_e32 v193, v193, v197
	v_cvt_pk_bf16_f32 v232, v190, v191
	v_cvt_pk_bf16_f32 v233, v192, v193
	v_fma_f32 v190, v86, v122, v118
	v_fma_f32 v191, v87, v123, v119
	v_fma_f32 v192, v88, v124, v120
	v_fma_f32 v193, v89, v125, v121
	v_fma_f32 v194, v82, v106, v102
	v_fma_f32 v195, v83, v107, v103
	v_fma_f32 v196, v84, v108, v104
	v_fma_f32 v197, v85, v109, v105
	v_fmac_f32_e32 v190, v94, v126
	v_fmac_f32_e32 v191, v95, v127
	v_fmac_f32_e32 v192, v96, v128
	v_fmac_f32_e32 v193, v97, v129
	v_fmac_f32_e32 v194, v90, v110
	v_fmac_f32_e32 v195, v91, v111
	v_fmac_f32_e32 v196, v92, v112
	v_fmac_f32_e32 v197, v93, v113
	v_fmac_f32_e32 v190, v78, v114
	v_fmac_f32_e32 v191, v79, v115
	v_fmac_f32_e32 v192, v80, v116
	v_fmac_f32_e32 v193, v81, v117
	v_fmac_f32_e32 v194, v74, v98
	v_fmac_f32_e32 v195, v75, v99
	v_fmac_f32_e32 v196, v76, v100
	v_fmac_f32_e32 v197, v77, v101
	v_mul_f32_e32 v198, 0xbfb8aa3b, v190
	v_mul_f32_e32 v199, 0xbfb8aa3b, v191
	v_mul_f32_e32 v200, 0xbfb8aa3b, v192
	v_mul_f32_e32 v201, 0xbfb8aa3b, v193
	v_exp_f32_e32 v198, v198
	v_exp_f32_e32 v199, v199
	v_exp_f32_e32 v200, v200
	v_exp_f32_e32 v201, v201
	v_add_f32_e32 v198, 1.0, v198
	v_add_f32_e32 v199, 1.0, v199
	v_add_f32_e32 v200, 1.0, v200
	v_add_f32_e32 v201, 1.0, v201
	v_rcp_f32_e32 v198, v198
	v_rcp_f32_e32 v199, v199
	v_rcp_f32_e32 v200, v200
	v_rcp_f32_e32 v201, v201
	v_mul_f32_e32 v190, v190, v198
	v_mul_f32_e32 v191, v191, v199
	v_mul_f32_e32 v192, v192, v200
	v_mul_f32_e32 v193, v193, v201
	v_mul_f32_e32 v190, v190, v194
	v_mul_f32_e32 v191, v191, v195
	v_mul_f32_e32 v192, v192, v196
	v_mul_f32_e32 v193, v193, v197
	v_cvt_pk_bf16_f32 v234, v190, v191
	v_cvt_pk_bf16_f32 v235, v192, v193
	v_cmp_gt_i32_e32 vcc, s3, v230
	s_and_b64 vcc, vcc, s[52:53]
	s_nop 0
	v_permlane16_swap_b32_e32 v232, v234
	v_permlane16_swap_b32_e32 v233, v235
	s_and_saveexec_b64 s[0:1], vcc
	global_store_dwordx4 v231, v[232:235], s[12:13]
	s_mov_b64 exec, s[0:1]
	v_fma_f32 v190, v78, v122, v118
	v_fma_f32 v191, v79, v123, v119
	v_fma_f32 v192, v80, v124, v120
	v_fma_f32 v193, v81, v125, v121
	v_fma_f32 v194, v74, v106, v102
	v_fma_f32 v195, v75, v107, v103
	v_fma_f32 v196, v76, v108, v104
	v_fma_f32 v197, v77, v109, v105
	v_add_u32_e32 v230, 0x7e, v186
	v_add_u32_e32 v231, 0xad400, v187
	v_fmac_f32_e32 v190, v86, v126
	v_fmac_f32_e32 v191, v87, v127
	v_fmac_f32_e32 v192, v88, v128
	v_fmac_f32_e32 v193, v89, v129
	v_fmac_f32_e32 v194, v82, v110
	v_fmac_f32_e32 v195, v83, v111
	v_fmac_f32_e32 v196, v84, v112
	v_fmac_f32_e32 v197, v85, v113
	v_fmac_f32_e32 v190, v70, v114
	v_fmac_f32_e32 v191, v71, v115
	v_fmac_f32_e32 v192, v72, v116
	v_fmac_f32_e32 v193, v73, v117
	v_fmac_f32_e32 v194, v66, v98
	v_fmac_f32_e32 v195, v67, v99
	v_fmac_f32_e32 v196, v68, v100
	v_fmac_f32_e32 v197, v69, v101
	v_mul_f32_e32 v198, 0xbfb8aa3b, v190
	v_mul_f32_e32 v199, 0xbfb8aa3b, v191
	v_mul_f32_e32 v200, 0xbfb8aa3b, v192
	v_mul_f32_e32 v201, 0xbfb8aa3b, v193
	v_exp_f32_e32 v198, v198
	v_exp_f32_e32 v199, v199
	v_exp_f32_e32 v200, v200
	v_exp_f32_e32 v201, v201
	v_add_f32_e32 v198, 1.0, v198
	v_add_f32_e32 v199, 1.0, v199
	v_add_f32_e32 v200, 1.0, v200
	v_add_f32_e32 v201, 1.0, v201
	v_rcp_f32_e32 v198, v198
	v_rcp_f32_e32 v199, v199
	v_rcp_f32_e32 v200, v200
	v_rcp_f32_e32 v201, v201
	v_mul_f32_e32 v190, v190, v198
	v_mul_f32_e32 v191, v191, v199
	v_mul_f32_e32 v192, v192, v200
	v_mul_f32_e32 v193, v193, v201
	v_mul_f32_e32 v190, v190, v194
	v_mul_f32_e32 v191, v191, v195
	v_mul_f32_e32 v192, v192, v196
	v_mul_f32_e32 v193, v193, v197
	v_cvt_pk_bf16_f32 v232, v190, v191
	v_cvt_pk_bf16_f32 v233, v192, v193
	v_fma_f32 v190, v70, v122, v118
	v_fma_f32 v191, v71, v123, v119
	v_fma_f32 v192, v72, v124, v120
	v_fma_f32 v193, v73, v125, v121
	v_fma_f32 v194, v66, v106, v102
	v_fma_f32 v195, v67, v107, v103
	v_fma_f32 v196, v68, v108, v104
	v_fma_f32 v197, v69, v109, v105
	v_fmac_f32_e32 v190, v78, v126
	v_fmac_f32_e32 v191, v79, v127
	v_fmac_f32_e32 v192, v80, v128
	v_fmac_f32_e32 v193, v81, v129
	v_fmac_f32_e32 v194, v74, v110
	v_fmac_f32_e32 v195, v75, v111
	v_fmac_f32_e32 v196, v76, v112
	v_fmac_f32_e32 v197, v77, v113
	v_fmac_f32_dpp v190, v94, v114 row_ror:15 row_mask:0xf bank_mask:0xf
	v_fmac_f32_dpp v191, v95, v115 row_ror:15 row_mask:0xf bank_mask:0xf
	v_fmac_f32_dpp v192, v96, v116 row_ror:15 row_mask:0xf bank_mask:0xf
	v_fmac_f32_dpp v193, v97, v117 row_ror:15 row_mask:0xf bank_mask:0xf
	v_fmac_f32_dpp v194, v90, v98 row_ror:15 row_mask:0xf bank_mask:0xf
	v_fmac_f32_dpp v195, v91, v99 row_ror:15 row_mask:0xf bank_mask:0xf
	v_fmac_f32_dpp v196, v92, v100 row_ror:15 row_mask:0xf bank_mask:0xf
	v_fmac_f32_dpp v197, v93, v101 row_ror:15 row_mask:0xf bank_mask:0xf
	v_mul_f32_e32 v198, 0xbfb8aa3b, v190
	v_mul_f32_e32 v199, 0xbfb8aa3b, v191
	v_mul_f32_e32 v200, 0xbfb8aa3b, v192
	v_mul_f32_e32 v201, 0xbfb8aa3b, v193
	v_exp_f32_e32 v198, v198
	v_exp_f32_e32 v199, v199
	v_exp_f32_e32 v200, v200
	v_exp_f32_e32 v201, v201
	v_add_f32_e32 v198, 1.0, v198
	v_add_f32_e32 v199, 1.0, v199
	v_add_f32_e32 v200, 1.0, v200
	v_add_f32_e32 v201, 1.0, v201
	v_rcp_f32_e32 v198, v198
	v_rcp_f32_e32 v199, v199
	v_rcp_f32_e32 v200, v200
	v_rcp_f32_e32 v201, v201
	v_mul_f32_e32 v190, v190, v198
	v_mul_f32_e32 v191, v191, v199
	v_mul_f32_e32 v192, v192, v200
	v_mul_f32_e32 v193, v193, v201
	v_mul_f32_e32 v190, v190, v194
	v_mul_f32_e32 v191, v191, v195
	v_mul_f32_e32 v192, v192, v196
	v_mul_f32_e32 v193, v193, v197
	v_cvt_pk_bf16_f32 v234, v190, v191
	v_cvt_pk_bf16_f32 v235, v192, v193
	v_cmp_gt_i32_e32 vcc, s3, v230
	s_and_b64 vcc, vcc, s[54:55]
	s_nop 0
	v_permlane16_swap_b32_e32 v232, v234
	v_permlane16_swap_b32_e32 v233, v235
	s_and_saveexec_b64 s[0:1], vcc
	global_store_dwordx4 v231, v[232:235], s[12:13]
	s_mov_b64 exec, s[0:1]
	s_waitcnt lgkmcnt(0)
	v_fma_f32 v190, v62, v134, v142
	v_fma_f32 v191, v63, v135, v143
	v_fma_f32 v192, v64, v136, v144
	v_fma_f32 v193, v65, v137, v145
	v_fma_f32 v194, v58, v150, v158
	v_fma_f32 v195, v59, v151, v159
	v_fma_f32 v196, v60, v152, v160
	v_fma_f32 v197, v61, v153, v161
	v_add_u32_e32 v230, 0, v186
	v_fmac_f32_dpp v190, v38, v130 row_ror:1 row_mask:0xf bank_mask:0xf
	v_fmac_f32_dpp v191, v39, v131 row_ror:1 row_mask:0xf bank_mask:0xf
	v_fmac_f32_dpp v192, v40, v132 row_ror:1 row_mask:0xf bank_mask:0xf
	v_fmac_f32_dpp v193, v41, v133 row_ror:1 row_mask:0xf bank_mask:0xf
	v_fmac_f32_dpp v194, v34, v146 row_ror:1 row_mask:0xf bank_mask:0xf
	v_fmac_f32_dpp v195, v35, v147 row_ror:1 row_mask:0xf bank_mask:0xf
	v_fmac_f32_dpp v196, v36, v148 row_ror:1 row_mask:0xf bank_mask:0xf
	v_fmac_f32_dpp v197, v37, v149 row_ror:1 row_mask:0xf bank_mask:0xf
	v_fmac_f32_e32 v190, v54, v138
	v_fmac_f32_e32 v191, v55, v139
	v_fmac_f32_e32 v192, v56, v140
	v_fmac_f32_e32 v193, v57, v141
	v_fmac_f32_e32 v194, v50, v154
	v_fmac_f32_e32 v195, v51, v155
	v_fmac_f32_e32 v196, v52, v156
	v_fmac_f32_e32 v197, v53, v157
	v_mul_f32_e32 v198, 0xbfb8aa3b, v190
	v_mul_f32_e32 v199, 0xbfb8aa3b, v191
	v_mul_f32_e32 v200, 0xbfb8aa3b, v192
	v_mul_f32_e32 v201, 0xbfb8aa3b, v193
	v_exp_f32_e32 v198, v198
	v_exp_f32_e32 v199, v199
	v_exp_f32_e32 v200, v200
	v_exp_f32_e32 v201, v201
	v_add_f32_e32 v198, 1.0, v198
	v_add_f32_e32 v199, 1.0, v199
	v_add_f32_e32 v200, 1.0, v200
	v_add_f32_e32 v201, 1.0, v201
	v_rcp_f32_e32 v198, v198
	v_rcp_f32_e32 v199, v199
	v_rcp_f32_e32 v200, v200
	v_rcp_f32_e32 v201, v201
	v_mul_f32_e32 v190, v190, v198
	v_mul_f32_e32 v191, v191, v199
	v_mul_f32_e32 v192, v192, v200
	v_mul_f32_e32 v193, v193, v201
	v_mul_f32_e32 v190, v190, v194
	v_mul_f32_e32 v191, v191, v195
	v_mul_f32_e32 v192, v192, v196
	v_mul_f32_e32 v193, v193, v197
	v_cvt_pk_bf16_f32 v232, v190, v191
	v_cvt_pk_bf16_f32 v233, v192, v193
	v_fma_f32 v190, v54, v134, v142
	v_fma_f32 v191, v55, v135, v143
	v_fma_f32 v192, v56, v136, v144
	v_fma_f32 v193, v57, v137, v145
	v_fma_f32 v194, v50, v150, v158
	v_fma_f32 v195, v51, v151, v159
	v_fma_f32 v196, v52, v152, v160
	v_fma_f32 v197, v53, v153, v161
	v_fmac_f32_e32 v190, v62, v130
	v_fmac_f32_e32 v191, v63, v131
	v_fmac_f32_e32 v192, v64, v132
	v_fmac_f32_e32 v193, v65, v133
	v_fmac_f32_e32 v194, v58, v146
	v_fmac_f32_e32 v195, v59, v147
	v_fmac_f32_e32 v196, v60, v148
	v_fmac_f32_e32 v197, v61, v149
	v_fmac_f32_e32 v190, v46, v138
	v_fmac_f32_e32 v191, v47, v139
	v_fmac_f32_e32 v192, v48, v140
	v_fmac_f32_e32 v193, v49, v141
	v_fmac_f32_e32 v194, v42, v154
	v_fmac_f32_e32 v195, v43, v155
	v_fmac_f32_e32 v196, v44, v156
	v_fmac_f32_e32 v197, v45, v157
	v_mul_f32_e32 v198, 0xbfb8aa3b, v190
	v_mul_f32_e32 v199, 0xbfb8aa3b, v191
	v_mul_f32_e32 v200, 0xbfb8aa3b, v192
	v_mul_f32_e32 v201, 0xbfb8aa3b, v193
	v_exp_f32_e32 v198, v198
	v_exp_f32_e32 v199, v199
	v_exp_f32_e32 v200, v200
	v_exp_f32_e32 v201, v201
	v_add_f32_e32 v198, 1.0, v198
	v_add_f32_e32 v199, 1.0, v199
	v_add_f32_e32 v200, 1.0, v200
	v_add_f32_e32 v201, 1.0, v201
	v_rcp_f32_e32 v198, v198
	v_rcp_f32_e32 v199, v199
	v_rcp_f32_e32 v200, v200
	v_rcp_f32_e32 v201, v201
	v_mul_f32_e32 v190, v190, v198
	v_mul_f32_e32 v191, v191, v199
	v_mul_f32_e32 v192, v192, v200
	v_mul_f32_e32 v193, v193, v201
	v_mul_f32_e32 v190, v190, v194
	v_mul_f32_e32 v191, v191, v195
	v_mul_f32_e32 v192, v192, v196
	v_mul_f32_e32 v193, v193, v197
	v_cvt_pk_bf16_f32 v234, v190, v191
	v_cvt_pk_bf16_f32 v235, v192, v193
	v_cmp_gt_i32_e32 vcc, s3, v230
	s_and_b64 vcc, vcc, s[52:53]
	s_nop 0
	v_permlane16_swap_b32_e32 v232, v234
	v_permlane16_swap_b32_e32 v233, v235
	s_and_saveexec_b64 s[0:1], vcc
	global_store_dwordx4 v187, v[232:235], s[12:13] offset:128
	s_mov_b64 exec, s[0:1]
	v_fma_f32 v190, v46, v134, v142
	v_fma_f32 v191, v47, v135, v143
	v_fma_f32 v192, v48, v136, v144
	v_fma_f32 v193, v49, v137, v145
	v_fma_f32 v194, v42, v150, v158
	v_fma_f32 v195, v43, v151, v159
	v_fma_f32 v196, v44, v152, v160
	v_fma_f32 v197, v45, v153, v161
	v_add_u32_e32 v230, 2, v186
	v_add_u32_e32 v231, 0x2c00, v187
	v_fmac_f32_e32 v190, v54, v130
	v_fmac_f32_e32 v191, v55, v131
	v_fmac_f32_e32 v192, v56, v132
	v_fmac_f32_e32 v193, v57, v133
	v_fmac_f32_e32 v194, v50, v146
	v_fmac_f32_e32 v195, v51, v147
	v_fmac_f32_e32 v196, v52, v148
	v_fmac_f32_e32 v197, v53, v149
	v_fmac_f32_e32 v190, v38, v138
	v_fmac_f32_e32 v191, v39, v139
	v_fmac_f32_e32 v192, v40, v140
	v_fmac_f32_e32 v193, v41, v141
	v_fmac_f32_e32 v194, v34, v154
	v_fmac_f32_e32 v195, v35, v155
	v_fmac_f32_e32 v196, v36, v156
	v_fmac_f32_e32 v197, v37, v157
	v_mul_f32_e32 v198, 0xbfb8aa3b, v190
	v_mul_f32_e32 v199, 0xbfb8aa3b, v191
	v_mul_f32_e32 v200, 0xbfb8aa3b, v192
	v_mul_f32_e32 v201, 0xbfb8aa3b, v193
	v_exp_f32_e32 v198, v198
	v_exp_f32_e32 v199, v199
	v_exp_f32_e32 v200, v200
	v_exp_f32_e32 v201, v201
	v_add_f32_e32 v198, 1.0, v198
	v_add_f32_e32 v199, 1.0, v199
	v_add_f32_e32 v200, 1.0, v200
	v_add_f32_e32 v201, 1.0, v201
	v_rcp_f32_e32 v198, v198
	v_rcp_f32_e32 v199, v199
	v_rcp_f32_e32 v200, v200
	v_rcp_f32_e32 v201, v201
	v_mul_f32_e32 v190, v190, v198
	v_mul_f32_e32 v191, v191, v199
	v_mul_f32_e32 v192, v192, v200
	v_mul_f32_e32 v193, v193, v201
	v_mul_f32_e32 v190, v190, v194
	v_mul_f32_e32 v191, v191, v195
	v_mul_f32_e32 v192, v192, v196
	v_mul_f32_e32 v193, v193, v197
	v_cvt_pk_bf16_f32 v232, v190, v191
	v_cvt_pk_bf16_f32 v233, v192, v193
	v_fma_f32 v190, v38, v134, v142
	v_fma_f32 v191, v39, v135, v143
	v_fma_f32 v192, v40, v136, v144
	v_fma_f32 v193, v41, v137, v145
	v_fma_f32 v194, v34, v150, v158
	v_fma_f32 v195, v35, v151, v159
	v_fma_f32 v196, v36, v152, v160
	v_fma_f32 v197, v37, v153, v161
	v_fmac_f32_e32 v190, v46, v130
	v_fmac_f32_e32 v191, v47, v131
	v_fmac_f32_e32 v192, v48, v132
	v_fmac_f32_e32 v193, v49, v133
	v_fmac_f32_e32 v194, v42, v146
	v_fmac_f32_e32 v195, v43, v147
	v_fmac_f32_e32 v196, v44, v148
	v_fmac_f32_e32 v197, v45, v149
	v_fmac_f32_dpp v190, v62, v138 row_ror:15 row_mask:0xf bank_mask:0xf
	v_fmac_f32_dpp v191, v63, v139 row_ror:15 row_mask:0xf bank_mask:0xf
	v_fmac_f32_dpp v192, v64, v140 row_ror:15 row_mask:0xf bank_mask:0xf
	v_fmac_f32_dpp v193, v65, v141 row_ror:15 row_mask:0xf bank_mask:0xf
	v_fmac_f32_dpp v194, v58, v154 row_ror:15 row_mask:0xf bank_mask:0xf
	v_fmac_f32_dpp v195, v59, v155 row_ror:15 row_mask:0xf bank_mask:0xf
	v_fmac_f32_dpp v196, v60, v156 row_ror:15 row_mask:0xf bank_mask:0xf
	v_fmac_f32_dpp v197, v61, v157 row_ror:15 row_mask:0xf bank_mask:0xf
	v_mul_f32_e32 v198, 0xbfb8aa3b, v190
	v_mul_f32_e32 v199, 0xbfb8aa3b, v191
	v_mul_f32_e32 v200, 0xbfb8aa3b, v192
	v_mul_f32_e32 v201, 0xbfb8aa3b, v193
	v_exp_f32_e32 v198, v198
	v_exp_f32_e32 v199, v199
	v_exp_f32_e32 v200, v200
	v_exp_f32_e32 v201, v201
	v_add_f32_e32 v198, 1.0, v198
	v_add_f32_e32 v199, 1.0, v199
	v_add_f32_e32 v200, 1.0, v200
	v_add_f32_e32 v201, 1.0, v201
	v_rcp_f32_e32 v198, v198
	v_rcp_f32_e32 v199, v199
	v_rcp_f32_e32 v200, v200
	v_rcp_f32_e32 v201, v201
	v_mul_f32_e32 v190, v190, v198
	v_mul_f32_e32 v191, v191, v199
	v_mul_f32_e32 v192, v192, v200
	v_mul_f32_e32 v193, v193, v201
	v_mul_f32_e32 v190, v190, v194
	v_mul_f32_e32 v191, v191, v195
	v_mul_f32_e32 v192, v192, v196
	v_mul_f32_e32 v193, v193, v197
	v_cvt_pk_bf16_f32 v234, v190, v191
	v_cvt_pk_bf16_f32 v235, v192, v193
	v_cmp_gt_i32_e32 vcc, s3, v230
	s_and_b64 vcc, vcc, s[54:55]
	s_nop 0
	v_permlane16_swap_b32_e32 v232, v234
	v_permlane16_swap_b32_e32 v233, v235
	s_and_saveexec_b64 s[0:1], vcc
	global_store_dwordx4 v231, v[232:235], s[12:13] offset:128
	s_mov_b64 exec, s[0:1]
	v_fma_f32 v190, v30, v134, v142
	v_fma_f32 v191, v31, v135, v143
	v_fma_f32 v192, v32, v136, v144
	v_fma_f32 v193, v33, v137, v145
	v_fma_f32 v194, v26, v150, v158
	v_fma_f32 v195, v27, v151, v159
	v_fma_f32 v196, v28, v152, v160
	v_fma_f32 v197, v29, v153, v161
	v_add_u32_e32 v230, 0x7c, v186
	v_add_u32_e32 v231, 0xaa800, v187
	v_fmac_f32_dpp v190, v6, v130 row_ror:1 row_mask:0xf bank_mask:0xf
	v_fmac_f32_dpp v191, v7, v131 row_ror:1 row_mask:0xf bank_mask:0xf
	v_fmac_f32_dpp v192, v8, v132 row_ror:1 row_mask:0xf bank_mask:0xf
	v_fmac_f32_dpp v193, v9, v133 row_ror:1 row_mask:0xf bank_mask:0xf
	v_fmac_f32_dpp v194, v2, v146 row_ror:1 row_mask:0xf bank_mask:0xf
	v_fmac_f32_dpp v195, v3, v147 row_ror:1 row_mask:0xf bank_mask:0xf
	v_fmac_f32_dpp v196, v4, v148 row_ror:1 row_mask:0xf bank_mask:0xf
	v_fmac_f32_dpp v197, v5, v149 row_ror:1 row_mask:0xf bank_mask:0xf
	v_fmac_f32_e32 v190, v22, v138
	v_fmac_f32_e32 v191, v23, v139
	v_fmac_f32_e32 v192, v24, v140
	v_fmac_f32_e32 v193, v25, v141
	v_fmac_f32_e32 v194, v18, v154
	v_fmac_f32_e32 v195, v19, v155
	v_fmac_f32_e32 v196, v20, v156
	v_fmac_f32_e32 v197, v21, v157
	v_mul_f32_e32 v198, 0xbfb8aa3b, v190
	v_mul_f32_e32 v199, 0xbfb8aa3b, v191
	v_mul_f32_e32 v200, 0xbfb8aa3b, v192
	v_mul_f32_e32 v201, 0xbfb8aa3b, v193
	v_exp_f32_e32 v198, v198
	v_exp_f32_e32 v199, v199
	v_exp_f32_e32 v200, v200
	v_exp_f32_e32 v201, v201
	v_add_f32_e32 v198, 1.0, v198
	v_add_f32_e32 v199, 1.0, v199
	v_add_f32_e32 v200, 1.0, v200
	v_add_f32_e32 v201, 1.0, v201
	v_rcp_f32_e32 v198, v198
	v_rcp_f32_e32 v199, v199
	v_rcp_f32_e32 v200, v200
	v_rcp_f32_e32 v201, v201
	v_mul_f32_e32 v190, v190, v198
	v_mul_f32_e32 v191, v191, v199
	v_mul_f32_e32 v192, v192, v200
	v_mul_f32_e32 v193, v193, v201
	v_mul_f32_e32 v190, v190, v194
	v_mul_f32_e32 v191, v191, v195
	v_mul_f32_e32 v192, v192, v196
	v_mul_f32_e32 v193, v193, v197
	v_cvt_pk_bf16_f32 v232, v190, v191
	v_cvt_pk_bf16_f32 v233, v192, v193
	v_fma_f32 v190, v22, v134, v142
	v_fma_f32 v191, v23, v135, v143
	v_fma_f32 v192, v24, v136, v144
	v_fma_f32 v193, v25, v137, v145
	v_fma_f32 v194, v18, v150, v158
	v_fma_f32 v195, v19, v151, v159
	v_fma_f32 v196, v20, v152, v160
	v_fma_f32 v197, v21, v153, v161
	v_fmac_f32_e32 v190, v30, v130
	v_fmac_f32_e32 v191, v31, v131
	v_fmac_f32_e32 v192, v32, v132
	v_fmac_f32_e32 v193, v33, v133
	v_fmac_f32_e32 v194, v26, v146
	v_fmac_f32_e32 v195, v27, v147
	v_fmac_f32_e32 v196, v28, v148
	v_fmac_f32_e32 v197, v29, v149
	v_fmac_f32_e32 v190, v14, v138
	v_fmac_f32_e32 v191, v15, v139
	v_fmac_f32_e32 v192, v16, v140
	v_fmac_f32_e32 v193, v17, v141
	v_fmac_f32_e32 v194, v10, v154
	v_fmac_f32_e32 v195, v11, v155
	v_fmac_f32_e32 v196, v12, v156
	v_fmac_f32_e32 v197, v13, v157
	v_mul_f32_e32 v198, 0xbfb8aa3b, v190
	v_mul_f32_e32 v199, 0xbfb8aa3b, v191
	v_mul_f32_e32 v200, 0xbfb8aa3b, v192
	v_mul_f32_e32 v201, 0xbfb8aa3b, v193
	v_exp_f32_e32 v198, v198
	v_exp_f32_e32 v199, v199
	v_exp_f32_e32 v200, v200
	v_exp_f32_e32 v201, v201
	v_add_f32_e32 v198, 1.0, v198
	v_add_f32_e32 v199, 1.0, v199
	v_add_f32_e32 v200, 1.0, v200
	v_add_f32_e32 v201, 1.0, v201
	v_rcp_f32_e32 v198, v198
	v_rcp_f32_e32 v199, v199
	v_rcp_f32_e32 v200, v200
	v_rcp_f32_e32 v201, v201
	v_mul_f32_e32 v190, v190, v198
	v_mul_f32_e32 v191, v191, v199
	v_mul_f32_e32 v192, v192, v200
	v_mul_f32_e32 v193, v193, v201
	v_mul_f32_e32 v190, v190, v194
	v_mul_f32_e32 v191, v191, v195
	v_mul_f32_e32 v192, v192, v196
	v_mul_f32_e32 v193, v193, v197
	v_cvt_pk_bf16_f32 v234, v190, v191
	v_cvt_pk_bf16_f32 v235, v192, v193
	v_cmp_gt_i32_e32 vcc, s3, v230
	s_and_b64 vcc, vcc, s[52:53]
	s_nop 0
	v_permlane16_swap_b32_e32 v232, v234
	v_permlane16_swap_b32_e32 v233, v235
	s_and_saveexec_b64 s[0:1], vcc
	global_store_dwordx4 v231, v[232:235], s[12:13] offset:128
	s_mov_b64 exec, s[0:1]
	v_fma_f32 v190, v14, v134, v142
	v_fma_f32 v191, v15, v135, v143
	v_fma_f32 v192, v16, v136, v144
	v_fma_f32 v193, v17, v137, v145
	v_fma_f32 v194, v10, v150, v158
	v_fma_f32 v195, v11, v151, v159
	v_fma_f32 v196, v12, v152, v160
	v_fma_f32 v197, v13, v153, v161
	v_add_u32_e32 v230, 0x7e, v186
	v_add_u32_e32 v231, 0xad400, v187
	v_fmac_f32_e32 v190, v22, v130
	v_fmac_f32_e32 v191, v23, v131
	v_fmac_f32_e32 v192, v24, v132
	v_fmac_f32_e32 v193, v25, v133
	v_fmac_f32_e32 v194, v18, v146
	v_fmac_f32_e32 v195, v19, v147
	v_fmac_f32_e32 v196, v20, v148
	v_fmac_f32_e32 v197, v21, v149
	v_fmac_f32_e32 v190, v6, v138
	v_fmac_f32_e32 v191, v7, v139
	v_fmac_f32_e32 v192, v8, v140
	v_fmac_f32_e32 v193, v9, v141
	v_fmac_f32_e32 v194, v2, v154
	v_fmac_f32_e32 v195, v3, v155
	v_fmac_f32_e32 v196, v4, v156
	v_fmac_f32_e32 v197, v5, v157
	v_mul_f32_e32 v198, 0xbfb8aa3b, v190
	v_mul_f32_e32 v199, 0xbfb8aa3b, v191
	v_mul_f32_e32 v200, 0xbfb8aa3b, v192
	v_mul_f32_e32 v201, 0xbfb8aa3b, v193
	v_exp_f32_e32 v198, v198
	v_exp_f32_e32 v199, v199
	v_exp_f32_e32 v200, v200
	v_exp_f32_e32 v201, v201
	v_add_f32_e32 v198, 1.0, v198
	v_add_f32_e32 v199, 1.0, v199
	v_add_f32_e32 v200, 1.0, v200
	v_add_f32_e32 v201, 1.0, v201
	v_rcp_f32_e32 v198, v198
	v_rcp_f32_e32 v199, v199
	v_rcp_f32_e32 v200, v200
	v_rcp_f32_e32 v201, v201
	v_mul_f32_e32 v190, v190, v198
	v_mul_f32_e32 v191, v191, v199
	v_mul_f32_e32 v192, v192, v200
	v_mul_f32_e32 v193, v193, v201
	v_mul_f32_e32 v190, v190, v194
	v_mul_f32_e32 v191, v191, v195
	v_mul_f32_e32 v192, v192, v196
	v_mul_f32_e32 v193, v193, v197
	v_cvt_pk_bf16_f32 v232, v190, v191
	v_cvt_pk_bf16_f32 v233, v192, v193
	v_fma_f32 v190, v6, v134, v142
	v_fma_f32 v191, v7, v135, v143
	v_fma_f32 v192, v8, v136, v144
	v_fma_f32 v193, v9, v137, v145
	v_fma_f32 v194, v2, v150, v158
	v_fma_f32 v195, v3, v151, v159
	v_fma_f32 v196, v4, v152, v160
	v_fma_f32 v197, v5, v153, v161
	v_fmac_f32_e32 v190, v14, v130
	v_fmac_f32_e32 v191, v15, v131
	v_fmac_f32_e32 v192, v16, v132
	v_fmac_f32_e32 v193, v17, v133
	v_fmac_f32_e32 v194, v10, v146
	v_fmac_f32_e32 v195, v11, v147
	v_fmac_f32_e32 v196, v12, v148
	v_fmac_f32_e32 v197, v13, v149
	v_fmac_f32_dpp v190, v30, v138 row_ror:15 row_mask:0xf bank_mask:0xf
	v_fmac_f32_dpp v191, v31, v139 row_ror:15 row_mask:0xf bank_mask:0xf
	v_fmac_f32_dpp v192, v32, v140 row_ror:15 row_mask:0xf bank_mask:0xf
	v_fmac_f32_dpp v193, v33, v141 row_ror:15 row_mask:0xf bank_mask:0xf
	v_fmac_f32_dpp v194, v26, v154 row_ror:15 row_mask:0xf bank_mask:0xf
	v_fmac_f32_dpp v195, v27, v155 row_ror:15 row_mask:0xf bank_mask:0xf
	v_fmac_f32_dpp v196, v28, v156 row_ror:15 row_mask:0xf bank_mask:0xf
	v_fmac_f32_dpp v197, v29, v157 row_ror:15 row_mask:0xf bank_mask:0xf
	v_mul_f32_e32 v198, 0xbfb8aa3b, v190
	v_mul_f32_e32 v199, 0xbfb8aa3b, v191
	v_mul_f32_e32 v200, 0xbfb8aa3b, v192
	v_mul_f32_e32 v201, 0xbfb8aa3b, v193
	v_exp_f32_e32 v198, v198
	v_exp_f32_e32 v199, v199
	v_exp_f32_e32 v200, v200
	v_exp_f32_e32 v201, v201
	v_add_f32_e32 v198, 1.0, v198
	v_add_f32_e32 v199, 1.0, v199
	v_add_f32_e32 v200, 1.0, v200
	v_add_f32_e32 v201, 1.0, v201
	v_rcp_f32_e32 v198, v198
	v_rcp_f32_e32 v199, v199
	v_rcp_f32_e32 v200, v200
	v_rcp_f32_e32 v201, v201
	v_mul_f32_e32 v190, v190, v198
	v_mul_f32_e32 v191, v191, v199
	v_mul_f32_e32 v192, v192, v200
	v_mul_f32_e32 v193, v193, v201
	v_mul_f32_e32 v190, v190, v194
	v_mul_f32_e32 v191, v191, v195
	v_mul_f32_e32 v192, v192, v196
	v_mul_f32_e32 v193, v193, v197
	v_cvt_pk_bf16_f32 v234, v190, v191
	v_cvt_pk_bf16_f32 v235, v192, v193
	v_cmp_gt_i32_e32 vcc, s3, v230
	s_and_b64 vcc, vcc, s[54:55]
	s_nop 0
	v_permlane16_swap_b32_e32 v232, v234
	v_permlane16_swap_b32_e32 v233, v235
	s_and_saveexec_b64 s[0:1], vcc
	global_store_dwordx4 v231, v[232:235], s[12:13] offset:128
	s_mov_b64 exec, s[0:1]
